# P1 K-loop software pipelined: every fragment ds_read and LDS-DMA issue placed between two MFMAs (ks1 reads in ks0 burst, next-step ks0 reads + DMA in ks1 burst), barrier mid-step
# speedup vs baseline: 1.0441x; 1.0046x over previous
.LBB0_381:
	s_lshr_b32 s2, s2, 6
	s_lshl_b32 s27, s2, 5
	v_or_b32_e32 v2, s27, v129
	v_add_u32_e32 v0, s3, v2
	s_or_b32 s40, s27, 16
	v_ashrrev_i32_e32 v1, 31, v0
	s_lshl_b32 s2, s2, 11
	v_add_u32_e32 v2, s24, v2
	v_or_b32_e32 v6, s40, v129
	v_lshlrev_b64 v[0:1], 11, v[0:1]
	s_add_i32 s39, s2, 0
	v_ashrrev_i32_e32 v3, 31, v2
	v_add_u32_e32 v4, s3, v6
	v_lshl_add_u64 v[0:1], v[142:143], 0, v[0:1]
	s_mov_b32 m0, s39
	v_lshlrev_b64 v[2:3], 11, v[2:3]
	v_ashrrev_i32_e32 v5, 31, v4
	s_lshl_b32 s3, s40, 6
	v_add_u32_e32 v6, s24, v6
	s_waitcnt lgkmcnt(0)
	s_barrier
	global_load_lds_dwordx4 v[0:1], off
	v_lshl_add_u64 v[2:3], v[144:145], 0, v[2:3]
	s_add_i32 m0, s39, 0x4000
	v_lshlrev_b64 v[4:5], 11, v[4:5]
	s_add_i32 s40, s3, 0
	v_ashrrev_i32_e32 v7, 31, v6
	global_load_lds_dwordx4 v[2:3], off
	v_lshl_add_u64 v[4:5], v[142:143], 0, v[4:5]
	s_mov_b32 m0, s40
	v_lshlrev_b64 v[6:7], 11, v[6:7]
	global_load_lds_dwordx4 v[4:5], off
	v_lshl_add_u64 v[6:7], v[144:145], 0, v[6:7]
	s_add_i32 m0, s40, 0x4000
	v_lshl_add_u64 v[8:9], v[0:1], 0, 64
	global_load_lds_dwordx4 v[6:7], off
	s_add_i32 m0, s39, 0x8000
	v_lshl_add_u64 v[0:1], v[0:1], 0, s[12:13]
	global_load_lds_dwordx4 v[8:9], off
	v_lshl_add_u64 v[8:9], v[2:3], 0, 64
	s_add_i32 m0, s39, 0xc000
	s_add_i32 s24, s27, s24
	global_load_lds_dwordx4 v[8:9], off
	v_lshl_add_u64 v[8:9], v[4:5], 0, 64
	s_add_i32 m0, s40, 0x8000
	s_add_i32 s23, s23, s22
	global_load_lds_dwordx4 v[8:9], off
	v_lshl_add_u64 v[8:9], v[6:7], 0, 64
	s_add_i32 m0, s40, 0xc000
	s_lshl_b32 s22, s23, 8
	global_load_lds_dwordx4 v[8:9], off
	s_add_i32 m0, s28, s2
	s_add_i32 s27, s27, s22
	global_load_lds_dwordx4 v[0:1], off
	v_lshl_add_u64 v[0:1], v[2:3], 0, s[12:13]
	s_add_i32 m0, s29, s2
	v_lshl_or_b32 v195, s25, 13, v189
	global_load_lds_dwordx4 v[0:1], off
	v_lshl_add_u64 v[0:1], v[4:5], 0, s[12:13]
	s_add_i32 m0, s28, s3
	s_mov_b64 s[22:23], 0
	global_load_lds_dwordx4 v[0:1], off
	v_lshl_add_u64 v[0:1], v[6:7], 0, s[12:13]
	s_add_i32 m0, s29, s3
	s_mov_b32 s39, 1
	global_load_lds_dwordx4 v[0:1], off
	v_or_b32_e32 v0, s26, v132
	v_lshlrev_b32_e32 v140, 6, v0
	v_add_u32_e32 v0, s24, v137
	v_ashrrev_i32_e32 v1, 31, v0
	v_lshlrev_b64 v[0:1], 11, v[0:1]
	v_lshl_add_u64 v[180:181], v[146:147], 0, v[0:1]
	v_or_b32_e32 v0, s27, v137
	v_ashrrev_i32_e32 v1, 31, v0
	v_lshlrev_b64 v[0:1], 11, v[0:1]
	v_lshl_add_u64 v[182:183], v[146:147], 0, v[0:1]
	v_add_u32_e32 v0, s24, v129
	v_ashrrev_i32_e32 v1, 31, v0
	v_lshlrev_b64 v[0:1], 11, v[0:1]
	v_lshl_add_u64 v[184:185], v[146:147], 0, v[0:1]
	v_or_b32_e32 v0, s27, v129
	v_ashrrev_i32_e32 v1, 31, v0
	v_lshlrev_b64 v[0:1], 11, v[0:1]
	v_lshl_add_u64 v[186:187], v[146:147], 0, v[0:1]
	s_mov_b32 s51, 0x18000
	s_add_i32 s55, s51, s2
	s_add_i32 s54, s51, s3
	s_mov_b32 m0, s55
	v_lshl_add_u64 v[198:199], v[186:187], 0, s[14:15]
	global_load_lds_dwordx4 v[198:199], off
	s_add_i32 m0, s55, 0x4000
	v_lshl_add_u64 v[198:199], v[184:185], 0, s[16:17]
	global_load_lds_dwordx4 v[198:199], off
	s_mov_b32 m0, s54
	v_lshl_add_u64 v[198:199], v[182:183], 0, s[14:15]
	global_load_lds_dwordx4 v[198:199], off
	s_add_i32 m0, s54, 0x4000
	v_lshl_add_u64 v[198:199], v[180:181], 0, s[16:17]
	global_load_lds_dwordx4 v[198:199], off
	v_mov_b32_e32 v0, 0
	s_mov_b32 s40, 0
	v_mov_b32_e32 v1, v0
	v_mov_b32_e32 v2, v0
	v_mov_b32_e32 v3, v0
	v_mov_b32_e32 v4, v0
	v_mov_b32_e32 v5, v0
	v_mov_b32_e32 v6, v0
	v_mov_b32_e32 v7, v0
	v_mov_b32_e32 v8, v0
	v_mov_b32_e32 v9, v0
	v_mov_b32_e32 v10, v0
	v_mov_b32_e32 v11, v0
	v_mov_b32_e32 v12, v0
	v_mov_b32_e32 v13, v0
	v_mov_b32_e32 v14, v0
	v_mov_b32_e32 v15, v0
	v_mov_b32_e32 v16, v0
	v_mov_b32_e32 v17, v0
	v_mov_b32_e32 v18, v0
	v_mov_b32_e32 v19, v0
	v_mov_b32_e32 v20, v0
	v_mov_b32_e32 v21, v0
	v_mov_b32_e32 v22, v0
	v_mov_b32_e32 v23, v0
	v_mov_b32_e32 v24, v0
	v_mov_b32_e32 v25, v0
	v_mov_b32_e32 v26, v0
	v_mov_b32_e32 v27, v0
	v_mov_b32_e32 v28, v0
	v_mov_b32_e32 v29, v0
	v_mov_b32_e32 v30, v0
	v_mov_b32_e32 v31, v0
	v_mov_b32_e32 v32, v0
	v_mov_b32_e32 v33, v0
	v_mov_b32_e32 v34, v0
	v_mov_b32_e32 v35, v0
	v_mov_b32_e32 v36, v0
	v_mov_b32_e32 v37, v0
	v_mov_b32_e32 v38, v0
	v_mov_b32_e32 v39, v0
	v_mov_b32_e32 v40, v0
	v_mov_b32_e32 v41, v0
	v_mov_b32_e32 v42, v0
	v_mov_b32_e32 v43, v0
	v_mov_b32_e32 v44, v0
	v_mov_b32_e32 v45, v0
	v_mov_b32_e32 v46, v0
	v_mov_b32_e32 v47, v0
	v_mov_b32_e32 v48, v0
	v_mov_b32_e32 v49, v0
	v_mov_b32_e32 v50, v0
	v_mov_b32_e32 v51, v0
	v_mov_b32_e32 v52, v0
	v_mov_b32_e32 v53, v0
	v_mov_b32_e32 v54, v0
	v_mov_b32_e32 v55, v0
	v_mov_b32_e32 v56, v0
	v_mov_b32_e32 v57, v0
	v_mov_b32_e32 v58, v0
	v_mov_b32_e32 v59, v0
	v_mov_b32_e32 v60, v0
	v_mov_b32_e32 v61, v0
	v_mov_b32_e32 v62, v0
	v_mov_b32_e32 v63, v0
	v_mov_b32_e32 v64, v0
	v_mov_b32_e32 v65, v0
	v_mov_b32_e32 v66, v0
	v_mov_b32_e32 v67, v0
	v_mov_b32_e32 v68, v0
	v_mov_b32_e32 v69, v0
	v_mov_b32_e32 v70, v0
	v_mov_b32_e32 v71, v0
	v_mov_b32_e32 v72, v0
	v_mov_b32_e32 v73, v0
	v_mov_b32_e32 v74, v0
	v_mov_b32_e32 v75, v0
	v_mov_b32_e32 v76, v0
	v_mov_b32_e32 v77, v0
	v_mov_b32_e32 v78, v0
	v_mov_b32_e32 v79, v0
	v_mov_b32_e32 v80, v0
	v_mov_b32_e32 v81, v0
	v_mov_b32_e32 v82, v0
	v_mov_b32_e32 v83, v0
	v_mov_b32_e32 v84, v0
	v_mov_b32_e32 v85, v0
	v_mov_b32_e32 v86, v0
	v_mov_b32_e32 v87, v0
	v_mov_b32_e32 v88, v0
	v_mov_b32_e32 v89, v0
	v_mov_b32_e32 v90, v0
	v_mov_b32_e32 v91, v0
	v_mov_b32_e32 v92, v0
	v_mov_b32_e32 v93, v0
	v_mov_b32_e32 v94, v0
	v_mov_b32_e32 v95, v0
	s_waitcnt vmcnt(12)
	v_mov_b32_e32 v96, v0
	v_mov_b32_e32 v97, v0
	v_mov_b32_e32 v98, v0
	v_mov_b32_e32 v99, v0
	v_mov_b32_e32 v100, v0
	v_mov_b32_e32 v101, v0
	v_mov_b32_e32 v102, v0
	v_mov_b32_e32 v103, v0
	v_mov_b32_e32 v104, v0
	v_mov_b32_e32 v105, v0
	v_mov_b32_e32 v106, v0
	v_mov_b32_e32 v107, v0
	v_mov_b32_e32 v108, v0
	v_mov_b32_e32 v109, v0
	v_mov_b32_e32 v110, v0
	v_mov_b32_e32 v111, v0
	v_mov_b32_e32 v112, v0
	v_mov_b32_e32 v113, v0
	v_mov_b32_e32 v114, v0
	v_mov_b32_e32 v115, v0
	v_mov_b32_e32 v116, v0
	v_mov_b32_e32 v117, v0
	v_mov_b32_e32 v118, v0
	v_mov_b32_e32 v119, v0
	v_mov_b32_e32 v120, v0
	v_mov_b32_e32 v121, v0
	v_mov_b32_e32 v122, v0
	v_mov_b32_e32 v123, v0
	v_mov_b32_e32 v124, v0
	v_mov_b32_e32 v125, v0
	v_mov_b32_e32 v126, v0
	v_mov_b32_e32 v127, v0
	s_barrier
	v_add_u32_e32 v196, v188, v140
	v_add_u32_e32 v209, v188, v195
	ds_read_b128 v[214:217], v196 offset:2048
	ds_read_b128 v[210:213], v209 offset:16384
	ds_read_b128 v[218:221], v209 offset:18432
	ds_read_b128 v[222:225], v209 offset:20480
	ds_read_b128 v[226:229], v209 offset:22528
	ds_read_b128 v[196:199], v196
.Lq2_even:
	s_and_b32 s51, s40, 0x10000
	s_waitcnt lgkmcnt(4)
	v_mfma_f32_32x32x16_bf16 v[48:63], v[214:217], v[210:213], v[48:63]
	v_add_u32_e32 v255, s51, v190
	v_add_u32_e32 v230, v255, v140
	v_add_u32_e32 v255, v255, v195
	ds_read_b128 v[238:241], v230 offset:2048
	s_waitcnt lgkmcnt(4)
	v_mfma_f32_32x32x16_bf16 v[32:47], v[214:217], v[218:221], v[32:47]
	ds_read_b128 v[234:237], v255 offset:16384
	s_waitcnt lgkmcnt(4)
	v_mfma_f32_32x32x16_bf16 v[16:31], v[214:217], v[222:225], v[16:31]
	ds_read_b128 v[242:245], v255 offset:18432
	s_waitcnt lgkmcnt(4)
	v_mfma_f32_32x32x16_bf16 v[0:15], v[214:217], v[226:229], v[0:15]
	ds_read_b128 v[246:249], v255 offset:20480
	s_waitcnt lgkmcnt(4)
	v_mfma_f32_32x32x16_bf16 v[112:127], v[196:199], v[210:213], v[112:127]
	ds_read_b128 v[250:253], v255 offset:22528
	v_mfma_f32_32x32x16_bf16 v[96:111], v[196:199], v[218:221], v[96:111]
	ds_read_b128 v[230:233], v230
	v_mfma_f32_32x32x16_bf16 v[80:95], v[196:199], v[222:225], v[80:95]
	v_mfma_f32_32x32x16_bf16 v[64:79], v[196:199], v[226:229], v[64:79]
	s_cmp_gt_u32 s39, 29
	s_cbranch_scc1 .Lq2_e_ws
	s_waitcnt vmcnt(8)
	s_branch .Lq2_e_wd

.Lq2_e_wd:
	s_cmp_gt_u32 s39, 28
	s_cselect_b64 vcc, 0, -1
	s_add_i32 s55, s51, s2
	s_add_i32 s54, s51, s3
	s_add_i32 s50, s40, 0x8000
	s_and_b32 s50, s50, 0x18000
	s_waitcnt lgkmcnt(0)
	s_barrier
	v_mfma_f32_32x32x16_bf16 v[48:63], v[238:241], v[234:237], v[48:63]
	v_add_u32_e32 v209, s50, v188
	v_add_u32_e32 v196, v209, v140
	v_add_u32_e32 v209, v209, v195
	s_cbranch_vccz .Lq2_e_d0
	v_lshl_add_u64 v[198:199], v[186:187], 0, s[22:23]
	s_mov_b32 m0, s55
	v_lshl_add_u64 v[198:199], v[198:199], 0, s[18:19]
	global_load_lds_dwordx4 v[198:199], off
.Lq2_e_d0:
	ds_read_b128 v[214:217], v196 offset:2048
	v_mfma_f32_32x32x16_bf16 v[32:47], v[238:241], v[242:245], v[32:47]
	s_cbranch_vccz .Lq2_e_d1
	v_lshl_add_u64 v[198:199], v[184:185], 0, s[22:23]
	s_add_i32 m0, s55, 0x4000
	v_lshl_add_u64 v[198:199], v[198:199], 0, s[20:21]
	global_load_lds_dwordx4 v[198:199], off
.Lq2_e_d1:
	ds_read_b128 v[210:213], v209 offset:16384
	v_mfma_f32_32x32x16_bf16 v[16:31], v[238:241], v[246:249], v[16:31]
	s_cbranch_vccz .Lq2_e_d2
	v_lshl_add_u64 v[198:199], v[182:183], 0, s[22:23]
	s_mov_b32 m0, s54
	v_lshl_add_u64 v[198:199], v[198:199], 0, s[18:19]
	global_load_lds_dwordx4 v[198:199], off
.Lq2_e_d2:
	ds_read_b128 v[218:221], v209 offset:18432
	v_mfma_f32_32x32x16_bf16 v[0:15], v[238:241], v[250:253], v[0:15]
	s_cbranch_vccz .Lq2_e_d3
	v_lshl_add_u64 v[198:199], v[180:181], 0, s[22:23]
	s_add_i32 m0, s54, 0x4000
	v_lshl_add_u64 v[198:199], v[198:199], 0, s[20:21]
	global_load_lds_dwordx4 v[198:199], off
.Lq2_e_d3:
	ds_read_b128 v[222:225], v209 offset:20480
	v_mfma_f32_32x32x16_bf16 v[112:127], v[230:233], v[234:237], v[112:127]
	ds_read_b128 v[226:229], v209 offset:22528
	v_mfma_f32_32x32x16_bf16 v[96:111], v[230:233], v[242:245], v[96:111]
	ds_read_b128 v[196:199], v196
	v_mfma_f32_32x32x16_bf16 v[80:95], v[230:233], v[246:249], v[80:95]
	v_mfma_f32_32x32x16_bf16 v[64:79], v[230:233], v[250:253], v[64:79]
	s_add_i32 s51, s40, 0x8000
	s_and_b32 s51, s51, 0x18000
	s_waitcnt lgkmcnt(4)
	v_mfma_f32_32x32x16_bf16 v[48:63], v[214:217], v[210:213], v[48:63]
	v_add_u32_e32 v255, s51, v190
	v_add_u32_e32 v230, v255, v140
	v_add_u32_e32 v255, v255, v195
	ds_read_b128 v[238:241], v230 offset:2048
	s_waitcnt lgkmcnt(4)
	v_mfma_f32_32x32x16_bf16 v[32:47], v[214:217], v[218:221], v[32:47]
	ds_read_b128 v[234:237], v255 offset:16384
	s_waitcnt lgkmcnt(4)
	v_mfma_f32_32x32x16_bf16 v[16:31], v[214:217], v[222:225], v[16:31]
	ds_read_b128 v[242:245], v255 offset:18432
	s_waitcnt lgkmcnt(4)
	v_mfma_f32_32x32x16_bf16 v[0:15], v[214:217], v[226:229], v[0:15]
	ds_read_b128 v[246:249], v255 offset:20480
	s_waitcnt lgkmcnt(4)
	v_mfma_f32_32x32x16_bf16 v[112:127], v[196:199], v[210:213], v[112:127]
	ds_read_b128 v[250:253], v255 offset:22528
	v_mfma_f32_32x32x16_bf16 v[96:111], v[196:199], v[218:221], v[96:111]
	ds_read_b128 v[230:233], v230
	v_mfma_f32_32x32x16_bf16 v[80:95], v[196:199], v[222:225], v[80:95]
	v_mfma_f32_32x32x16_bf16 v[64:79], v[196:199], v[226:229], v[64:79]
	s_cmp_eq_u32 s39, 31
	s_cbranch_scc1 .Lq2_last
	s_cmp_gt_u32 s39, 28
	s_cbranch_scc1 .Lq2_o_ws
	s_waitcnt vmcnt(8)
	s_branch .Lq2_o_wd

.Lq2_o_wd:
	s_cmp_gt_u32 s39, 27
	s_cselect_b64 vcc, 0, -1
	s_add_i32 s55, s51, s2
	s_add_i32 s54, s51, s3
	s_add_i32 s50, s40, 0x10000
	s_and_b32 s50, s50, 0x10000
	s_waitcnt lgkmcnt(0)
	s_barrier
	v_mfma_f32_32x32x16_bf16 v[48:63], v[238:241], v[234:237], v[48:63]
	v_add_u32_e32 v209, s50, v188
	v_add_u32_e32 v196, v209, v140
	v_add_u32_e32 v209, v209, v195
	s_cbranch_vccz .Lq2_o_d0
	v_lshl_add_u64 v[198:199], v[186:187], 0, s[22:23]
	s_mov_b32 m0, s55
	v_lshl_add_u64 v[198:199], v[198:199], 0, s[60:61]
	global_load_lds_dwordx4 v[198:199], off
.Lq2_o_d0:
	ds_read_b128 v[214:217], v196 offset:2048
	v_mfma_f32_32x32x16_bf16 v[32:47], v[238:241], v[242:245], v[32:47]
	s_cbranch_vccz .Lq2_o_d1
	v_lshl_add_u64 v[198:199], v[184:185], 0, s[22:23]
	s_add_i32 m0, s55, 0x4000
	v_lshl_add_u64 v[198:199], v[198:199], 0, s[62:63]
	global_load_lds_dwordx4 v[198:199], off
.Lq2_o_d1:
	ds_read_b128 v[210:213], v209 offset:16384
	v_mfma_f32_32x32x16_bf16 v[16:31], v[238:241], v[246:249], v[16:31]
	s_cbranch_vccz .Lq2_o_d2
	v_lshl_add_u64 v[198:199], v[182:183], 0, s[22:23]
	s_mov_b32 m0, s54
	v_lshl_add_u64 v[198:199], v[198:199], 0, s[60:61]
	global_load_lds_dwordx4 v[198:199], off
.Lq2_o_d2:
	ds_read_b128 v[218:221], v209 offset:18432
	v_mfma_f32_32x32x16_bf16 v[0:15], v[238:241], v[250:253], v[0:15]
	s_cbranch_vccz .Lq2_o_d3
	v_lshl_add_u64 v[198:199], v[180:181], 0, s[22:23]
	s_add_i32 m0, s54, 0x4000
	v_lshl_add_u64 v[198:199], v[198:199], 0, s[62:63]
	global_load_lds_dwordx4 v[198:199], off
.Lq2_o_d3:
	ds_read_b128 v[222:225], v209 offset:20480
	v_mfma_f32_32x32x16_bf16 v[112:127], v[230:233], v[234:237], v[112:127]
	ds_read_b128 v[226:229], v209 offset:22528
	v_mfma_f32_32x32x16_bf16 v[96:111], v[230:233], v[242:245], v[96:111]
	ds_read_b128 v[196:199], v196
	v_mfma_f32_32x32x16_bf16 v[80:95], v[230:233], v[246:249], v[80:95]
	v_mfma_f32_32x32x16_bf16 v[64:79], v[230:233], v[250:253], v[64:79]
	s_add_u32 s22, s22, 0x80
	s_addc_u32 s23, s23, 0
	s_add_i32 s39, s39, 2
	s_add_i32 s40, s40, 0x10000
	s_branch .Lq2_even
